# GLA scan: next-chunk q/k row loads via scalar base + 32-bit lane offsets instead of 64-bit VALU address chains
# baseline (speedup 1.0000x reference)
.LBB0_471:
	s_lshl_b32 s0, s0, 6
	s_add_i32 s2, s0, s1
	s_mul_i32 s100, s2, s92
	s_add_u32 s100, s10, s100
	s_addc_u32 s101, s11, 0
	v_mul_u32_u24_e32 v74, s92, v91
	v_lshl_add_u32 v74, v92, 4, v74
	v_add_u32_e32 v74, 0x2000, v74
	v_add_u32_e32 v75, 0x39000, v74
	v_add_u32_e32 v76, 0x72000, v74
	v_add_u32_e32 v77, 0xab000, v74
	v_add_u32_e32 v0, s2, v90
	v_mov_b64_e32 v[54:55], s[82:83]
	v_mad_i64_i32 v[54:55], s[0:1], v0, s92, v[54:55]
	s_ashr_i32 s16, s2, 6
	v_lshl_add_u64 v[54:55], v[54:55], 0, s[42:43]
	s_mov_b32 s15, s43
	s_ashr_i32 s17, s16, 31
	v_lshl_add_u64 v[54:55], v[54:55], 0, s[14:15]
	v_lshlrev_b32_e32 v0, 1, v83
	s_lshl_b64 s[0:1], s[16:17], 16
	v_lshl_add_u64 v[54:55], v[54:55], 0, v[0:1]
	s_add_u32 s0, s20, s0
	v_add_co_u32_e32 v54, vcc, s3, v54
	s_addc_u32 s1, s21, s1
	s_nop 0
	v_addc_co_u32_e32 v55, vcc, 0, v55, vcc
	v_lshl_add_u64 v[70:71], s[0:1], 0, v[84:85]
	v_add_co_u32_e32 v62, vcc, 0x1000, v70
	global_load_dwordx4 v[2:5], v74, s[100:101] offset:1024
	global_load_dwordx4 v[6:9], v74, s[100:101] offset:-4096
	v_addc_co_u32_e32 v63, vcc, 0, v71, vcc
	v_add_co_u32_e32 v66, vcc, 0x2000, v70
	global_load_dwordx4 v[10:13], v75, s[100:101] offset:1024
	global_load_dwordx4 v[14:17], v75, s[100:101] offset:-4096
	v_addc_co_u32_e32 v67, vcc, 0, v71, vcc
	global_load_dwordx4 v[18:21], v76, s[100:101] offset:1024
	global_load_dwordx4 v[22:25], v76, s[100:101] offset:-4096
	global_load_dwordx4 v[30:33], v77, s[100:101] offset:1024
	global_load_dwordx4 v[34:37], v77, s[100:101] offset:-4096
	s_nop 0
	global_load_dwordx4 v[54:57], v[54:55], off offset:1024
	s_nop 0
	global_load_dwordx4 v[58:61], v[70:71], off
	v_add_co_u32_e32 v70, vcc, 0x3000, v70
	global_load_dwordx4 v[62:65], v[62:63], off
	s_nop 0
	global_load_dwordx4 v[66:69], v[66:67], off
	v_addc_co_u32_e32 v71, vcc, 0, v71, vcc
	global_load_dwordx4 v[70:73], v[70:71], off
	s_and_saveexec_b64 s[18:19], s[6:7]
	s_cbranch_execz .LBB0_473
	s_lshl_b64 s[0:1], s[16:17], 11
	s_add_u32 s0, s22, s0
	s_addc_u32 s1, s23, s1
	v_ashrrev_i32_e32 v83, 31, v82
	v_lshl_add_u64 v[26:27], v[82:83], 2, s[0:1]
	global_load_dwordx4 v[26:29], v[26:27], off
